# xattn stage loop: ring-buffered ds_read of K fragments with counted lgkmcnt, V fragments prefetched before softmax (on top of O2 selection rewrite)
# speedup vs baseline: 1.4792x; 1.0042x over previous
; template <int DQK, int DV, int MODE, bool QNORM, int SK, int NQ> ...
;     ...
;             __builtin_amdgcn_s_setprio(1);
; #pragma unroll
;             for (int d0 = 0; d0 < DQK / 16; ++d0)
; #pragma unroll
;                 for (int sub = 0; sub < NSUB; ++sub) {
;                     const bf16x8 kf = *(const LAS bf16x8*)(sb + (sub * 32 + r32) * KP + hi * 16 + d0 * 32);
; #pragma unroll
;                     for (int qh = 0; qh < NQ; ++qh) sc[qh][sub] = __builtin_amdgcn_mfma_f32_32x32x16_bf16(kf, qf[qh][d0], sc[qh][sub], 0, 0, 0);
;                 }
;             }
;             __builtin_amdgcn_s_setprio(0);
; #pragma unroll
;             for (int sub = 0; sub < NSUB; ++sub) {
;                 const int st = NSUB * sg + sub;
;                 if (QNORM) {
; #pragma unroll
;                     for (int qh = 0; qh < NQ; ++qh)
; #pragma unroll
;                         for (int r = 0; r < 16; ++r) sc[qh][sub][r] = sc[qh][sub][r] * sscale[qh] - m_run[qh];
;                 }
;                 if (MODE == 0) {
;                     if (st * 32 + 31 > q0) {
; #pragma unroll
;                         for (int r = 0; r < 16; ++r) { if (st * 32 + crow(r, hi) > q0 + r32) {
; #pragma unroll
;                             for (int qh = 0; qh < NQ; ++qh) sc[qh][sub][r] = -INFINITY; } }
;                     }
;                 } else if (MODE == 1) {
;                     const unsigned w = sub ? wcur1 : wcur0;
; #pragma unroll
;                     for (int r = 0; r < 16; ++r) { if (((w >> crow(r, hi)) & 1u) == 0u) {
; #pragma unroll
;                         for (int qh = 0; qh < NQ; ++qh) sc[qh][sub][r] = -INFINITY; } }
;                 } else if (st >= nst_w) {
; #pragma unroll
;                     for (int qh = 0; qh < NQ; ++qh)
; #pragma unroll
;                         for (int r = 0; r < 16; ++r) sc[qh][sub][r] = -INFINITY;
;                 }
;             }
;             bf16x8 pf[NQ][NSUB][2];
; #pragma unroll
;             for (int qh = 0; qh < NQ; ++qh) {
;                 float tm = sc[qh][0][0];
; #pragma unroll
;                 for (int sub = 0; sub < NSUB; ++sub)
; #pragma unroll
;                     for (int r = 0; r < 16; ++r) tm = fmaxf(tm, sc[qh][sub][r]);
;                 tm = fmaxf(tm, __shfl_xor(tm, 32));
;                 if (__ballot(tm > 0.f) != 0ull) {
;                     const float dl = fmaxf(tm, 0.f); m_run[qh] += dl;
.LBB0_4653:
	s_or_b64 exec, exec, s[12:13]
	s_bitcmp1_b32 s15, 0
	s_cselect_b32 s12, 0x6a00, 0
	s_add_i32 s12, s12, 0
	s_setprio 1
	v_add3_u32 v1, s12, v180, v181
	ds_read_b128 v[66:69], v1
	ds_read_b128 v[192:195], v1 offset:32
	ds_read_b128 v[196:199], v1 offset:64
	ds_read_b128 v[200:203], v1 offset:96
	ds_read_b128 v[204:207], v1 offset:128
	ds_read_b128 v[208:211], v1 offset:160
	ds_read_b128 v[212:215], v1 offset:192
	s_waitcnt lgkmcnt(6)
	v_mfma_f32_32x32x16_bf16 v[66:81], v[66:69], v[142:145], 0
	s_waitcnt lgkmcnt(5)
	v_mfma_f32_32x32x16_bf16 v[66:81], v[192:195], v[138:141], v[66:81]
	ds_read_b128 v[192:195], v1 offset:224
	s_waitcnt lgkmcnt(5)
	v_mfma_f32_32x32x16_bf16 v[66:81], v[196:199], v[134:137], v[66:81]
	ds_read_b128 v[196:199], v1 offset:256
	s_waitcnt lgkmcnt(5)
	v_mfma_f32_32x32x16_bf16 v[66:81], v[200:203], v[126:129], v[66:81]
	ds_read_b128 v[200:203], v1 offset:288
	s_waitcnt lgkmcnt(5)
	v_mfma_f32_32x32x16_bf16 v[66:81], v[204:207], v[118:121], v[66:81]
	ds_read_b128 v[204:207], v1 offset:320
	s_waitcnt lgkmcnt(5)
	v_mfma_f32_32x32x16_bf16 v[66:81], v[208:211], v[110:113], v[66:81]
	ds_read_b128 v[208:211], v1 offset:352
	s_waitcnt lgkmcnt(5)
	v_mfma_f32_32x32x16_bf16 v[66:81], v[212:215], v[102:105], v[66:81]
	ds_read_b128 v[212:215], v1 offset:384
	s_waitcnt lgkmcnt(5)
	v_mfma_f32_32x32x16_bf16 v[66:81], v[192:195], v[130:133], v[66:81]
	ds_read_b128 v[192:195], v1 offset:416
	s_waitcnt lgkmcnt(5)
	v_mfma_f32_32x32x16_bf16 v[66:81], v[196:199], v[122:125], v[66:81]
	ds_read_b128 v[196:199], v1 offset:448
	s_waitcnt lgkmcnt(5)
	v_mfma_f32_32x32x16_bf16 v[66:81], v[200:203], v[114:117], v[66:81]
	ds_read_b128 v[200:203], v1 offset:480
	s_waitcnt lgkmcnt(5)
	v_mfma_f32_32x32x16_bf16 v[66:81], v[204:207], v[106:109], v[66:81]
	s_waitcnt lgkmcnt(4)
	v_mfma_f32_32x32x16_bf16 v[66:81], v[208:211], v[98:101], v[66:81]
	s_waitcnt lgkmcnt(3)
	v_mfma_f32_32x32x16_bf16 v[66:81], v[212:215], v[94:97], v[66:81]
	s_waitcnt lgkmcnt(2)
	v_mfma_f32_32x32x16_bf16 v[66:81], v[192:195], v[90:93], v[66:81]
	s_waitcnt lgkmcnt(1)
	v_mfma_f32_32x32x16_bf16 v[66:81], v[196:199], v[86:89], v[66:81]
	s_waitcnt lgkmcnt(0)
	v_mfma_f32_32x32x16_bf16 v[66:81], v[200:203], v[82:85], v[66:81]
	s_setprio 0
	v_add3_u32 v191, s12, v182, v181
	ds_read_b128 v[204:207], v191 offset:16896
	ds_read_b128 v[208:211], v191 offset:16928
	ds_read_b128 v[212:215], v191 offset:19456
	ds_read_b128 v[216:219], v191 offset:19488
	ds_read_b128 v[200:203], v191 offset:22016
	s_nop 4
	v_pk_fma_f32 v[66:67], v[170:171], v[66:67], v[172:173] op_sel_hi:[1,1,0] neg_lo:[0,0,1] neg_hi:[0,0,1]
	v_pk_fma_f32 v[68:69], v[170:171], v[68:69], v[172:173] op_sel_hi:[1,1,0] neg_lo:[0,0,1] neg_hi:[0,0,1]
	v_max_f32_e32 v1, v66, v67
	v_pk_fma_f32 v[70:71], v[170:171], v[70:71], v[172:173] op_sel_hi:[1,1,0] neg_lo:[0,0,1] neg_hi:[0,0,1]
	v_max3_f32 v1, v1, v68, v69
	v_pk_fma_f32 v[72:73], v[170:171], v[72:73], v[172:173] op_sel_hi:[1,1,0] neg_lo:[0,0,1] neg_hi:[0,0,1]
	v_max3_f32 v1, v1, v70, v71
	v_pk_fma_f32 v[74:75], v[170:171], v[74:75], v[172:173] op_sel_hi:[1,1,0] neg_lo:[0,0,1] neg_hi:[0,0,1]
	v_max3_f32 v1, v1, v72, v73
	v_pk_fma_f32 v[76:77], v[170:171], v[76:77], v[172:173] op_sel_hi:[1,1,0] neg_lo:[0,0,1] neg_hi:[0,0,1]
	v_max3_f32 v1, v1, v74, v75
	v_pk_fma_f32 v[78:79], v[170:171], v[78:79], v[172:173] op_sel_hi:[1,1,0] neg_lo:[0,0,1] neg_hi:[0,0,1]
	v_max3_f32 v1, v1, v76, v77
	v_pk_fma_f32 v[80:81], v[170:171], v[80:81], v[172:173] op_sel_hi:[1,1,0] neg_lo:[0,0,1] neg_hi:[0,0,1]
	v_max3_f32 v1, v1, v78, v79
	v_max3_f32 v1, v1, v80, v81
	ds_bpermute_b32 v167, v222, v1
	s_waitcnt lgkmcnt(0)
	v_max_f32_e32 v167, v167, v167
	v_max_f32_e32 v1, v1, v167
	v_cmp_lt_f32_e32 vcc, 0, v1
	s_cbranch_vccz .LBB0_4655
	v_max_f32_e32 v1, v1, v1
	v_max_f32_e32 v192, 0, v1
	v_exp_f32_e64 v194, -v192
	v_pk_add_f32 v[66:67], v[66:67], v[192:193] op_sel_hi:[1,0] neg_lo:[0,1] neg_hi:[0,1]
	v_pk_add_f32 v[68:69], v[68:69], v[192:193] op_sel_hi:[1,0] neg_lo:[0,1] neg_hi:[0,1]
	v_pk_add_f32 v[70:71], v[70:71], v[192:193] op_sel_hi:[1,0] neg_lo:[0,1] neg_hi:[0,1]
	v_pk_add_f32 v[72:73], v[72:73], v[192:193] op_sel_hi:[1,0] neg_lo:[0,1] neg_hi:[0,1]
	v_pk_add_f32 v[74:75], v[74:75], v[192:193] op_sel_hi:[1,0] neg_lo:[0,1] neg_hi:[0,1]
	v_pk_add_f32 v[76:77], v[76:77], v[192:193] op_sel_hi:[1,0] neg_lo:[0,1] neg_hi:[0,1]
	v_pk_add_f32 v[78:79], v[78:79], v[192:193] op_sel_hi:[1,0] neg_lo:[0,1] neg_hi:[0,1]
	v_pk_add_f32 v[80:81], v[80:81], v[192:193] op_sel_hi:[1,0] neg_lo:[0,1] neg_hi:[0,1]
	v_add_f32_e32 v172, v172, v192
	v_pk_mul_f32 v[64:65], v[64:65], v[194:195] op_sel_hi:[1,0]
	v_pk_mul_f32 v[62:63], v[62:63], v[194:195] op_sel_hi:[1,0]
	v_pk_mul_f32 v[60:61], v[60:61], v[194:195] op_sel_hi:[1,0]
	v_pk_mul_f32 v[58:59], v[58:59], v[194:195] op_sel_hi:[1,0]
	v_pk_mul_f32 v[56:57], v[56:57], v[194:195] op_sel_hi:[1,0]
	v_pk_mul_f32 v[54:55], v[54:55], v[194:195] op_sel_hi:[1,0]
	v_pk_mul_f32 v[52:53], v[52:53], v[194:195] op_sel_hi:[1,0]
	v_pk_mul_f32 v[50:51], v[50:51], v[194:195] op_sel_hi:[1,0]
	v_pk_mul_f32 v[48:49], v[48:49], v[194:195] op_sel_hi:[1,0]
	v_pk_mul_f32 v[46:47], v[46:47], v[194:195] op_sel_hi:[1,0]
	v_pk_mul_f32 v[44:45], v[44:45], v[194:195] op_sel_hi:[1,0]
	v_pk_mul_f32 v[42:43], v[42:43], v[194:195] op_sel_hi:[1,0]
	v_pk_mul_f32 v[40:41], v[40:41], v[194:195] op_sel_hi:[1,0]
	v_pk_mul_f32 v[38:39], v[38:39], v[194:195] op_sel_hi:[1,0]
	v_pk_mul_f32 v[36:37], v[36:37], v[194:195] op_sel_hi:[1,0]
	v_pk_mul_f32 v[34:35], v[34:35], v[194:195] op_sel_hi:[1,0]
	v_pk_mul_f32 v[32:33], v[32:33], v[194:195] op_sel_hi:[1,0]
	v_pk_mul_f32 v[30:31], v[30:31], v[194:195] op_sel_hi:[1,0]
	v_pk_mul_f32 v[28:29], v[28:29], v[194:195] op_sel_hi:[1,0]
	v_pk_mul_f32 v[26:27], v[26:27], v[194:195] op_sel_hi:[1,0]
	v_pk_mul_f32 v[24:25], v[24:25], v[194:195] op_sel_hi:[1,0]
	v_pk_mul_f32 v[22:23], v[22:23], v[194:195] op_sel_hi:[1,0]
	v_pk_mul_f32 v[20:21], v[20:21], v[194:195] op_sel_hi:[1,0]
	v_pk_mul_f32 v[18:19], v[18:19], v[194:195] op_sel_hi:[1,0]
	v_pk_mul_f32 v[16:17], v[16:17], v[194:195] op_sel_hi:[1,0]
	v_pk_mul_f32 v[14:15], v[14:15], v[194:195] op_sel_hi:[1,0]
	v_pk_mul_f32 v[12:13], v[12:13], v[194:195] op_sel_hi:[1,0]
	v_pk_mul_f32 v[10:11], v[10:11], v[194:195] op_sel_hi:[1,0]
	v_pk_mul_f32 v[8:9], v[8:9], v[194:195] op_sel_hi:[1,0]
	v_pk_mul_f32 v[6:7], v[6:7], v[194:195] op_sel_hi:[1,0]
	v_pk_mul_f32 v[4:5], v[4:5], v[194:195] op_sel_hi:[1,0]
	v_pk_mul_f32 v[2:3], v[2:3], v[194:195] op_sel_hi:[1,0]
	v_mul_f32_e32 v165, v165, v194
; template <int DQK, int DV, int MODE, bool QNORM, int SK, int NQ> ...
;     ...
;                 float ps = 0.f;
; #pragma unroll
;                 for (int sub = 0; sub < NSUB; ++sub)
; #pragma unroll
;                     for (int r = 0; r < 16; ++r) { sc[qh][sub][r] = __builtin_amdgcn_exp2f(sc[qh][sub][r]); ps += sc[qh][sub][r]; }
;                 l_run[qh] += ps;
; #pragma unroll
;                 for (int sub = 0; sub < NSUB; ++sub) {
;                     u32x4 p0, p1;
;                     p0.x = pg8::cvt_pk_bf16(sc[qh][sub][0], sc[qh][sub][1]); p0.y = pg8::cvt_pk_bf16(sc[qh][sub][2], sc[qh][sub][3]); p0.z = pg8::cvt_pk_bf16(sc[qh][sub][4], sc[qh][sub][5]); p0.w = pg8::cvt_pk_bf16(sc[qh][sub][6], sc[qh][sub][7]);
;                     p1.x = pg8::cvt_pk_bf16(sc[qh][sub][8], sc[qh][sub][9]); p1.y = pg8::cvt_pk_bf16(sc[qh][sub][10], sc[qh][sub][11]); p1.z = pg8::cvt_pk_bf16(sc[qh][sub][12], sc[qh][sub][13]); p1.w = pg8::cvt_pk_bf16(sc[qh][sub][14], sc[qh][sub][15]);
;                     pf[qh][sub][0] = __builtin_bit_cast(bf16x8, p0); pf[qh][sub][1] = __builtin_bit_cast(bf16x8, p1);
;                 }
;             }
;             if (NQ == 1 && DQK <= 96) {
;                 bf16x8 vfa[NSUB][DV / 32][2];
; #pragma unroll
;                 for (int sub = 0; sub < NSUB; ++sub)
; #pragma unroll
;                     for (int dt = 0; dt < DV / 32; ++dt) {
;                         const LAS unsigned char* vb = sb + KBYTES + r32 * VP + (sub * 32 + hi * 8) * 2 + dt * 32 * VP;
;                         vfa[sub][dt][0] = *(const LAS bf16x8*)(vb); vfa[sub][dt][1] = *(const LAS bf16x8*)(vb + 32);
;                     }
;                 asm volatile("s_waitcnt lgkmcnt(0)" ::: "memory");
;                 __builtin_amdgcn_sched_barrier(0);
;                 __builtin_amdgcn_s_setprio(1);
; #pragma unroll
;                 for (int sub = 0; sub < NSUB; ++sub)
; #pragma unroll
;                     for (int dt = 0; dt < DV / 32; ++dt) {
;                         o[0][dt] = __builtin_amdgcn_mfma_f32_32x32x16_bf16(vfa[sub][dt][0], pf[0][sub][0], o[0][dt], 0, 0, 0);
;                         o[0][dt] = __builtin_amdgcn_mfma_f32_32x32x16_bf16(vfa[sub][dt][1], pf[0][sub][1], o[0][dt], 0, 0, 0);
;                     }
;                 __builtin_amdgcn_s_setprio(0);
;             } else {
;             __builtin_amdgcn_s_setprio(1);
; #pragma unroll
.LBB0_4655:
	v_exp_f32_e32 v1, v66
	v_exp_f32_e32 v66, v67
	v_exp_f32_e32 v67, v68
	v_exp_f32_e32 v68, v69
	v_exp_f32_e32 v69, v70
	v_exp_f32_e32 v70, v71
	v_exp_f32_e32 v71, v72
	v_exp_f32_e32 v72, v73
	v_exp_f32_e32 v73, v74
	v_exp_f32_e32 v74, v75
	v_exp_f32_e32 v75, v76
	v_exp_f32_e32 v76, v77
	v_exp_f32_e32 v77, v78
	v_exp_f32_e32 v78, v79
	v_exp_f32_e32 v79, v80
	v_exp_f32_e32 v80, v81
	v_cvt_pk_bf16_f32 v192, v1, v66
	v_cvt_pk_bf16_f32 v193, v67, v68
	v_cvt_pk_bf16_f32 v194, v69, v70
	v_cvt_pk_bf16_f32 v195, v71, v72
	v_cvt_pk_bf16_f32 v196, v73, v74
	v_cvt_pk_bf16_f32 v197, v75, v76
	v_cvt_pk_bf16_f32 v198, v77, v78
	v_cvt_pk_bf16_f32 v199, v79, v80
	s_setprio 1
	v_add3_u32 v81, s12, v182, v181
	s_waitcnt lgkmcnt(0)
	v_mfma_f32_32x32x16_bf16 v[50:65], v[204:207], v[192:195], v[50:65]
	ds_read_b128 v[204:207], v191 offset:22048
	v_mfma_f32_32x32x16_bf16 v[50:65], v[208:211], v[196:199], v[50:65]
	ds_read_b128 v[208:211], v191 offset:24576
	v_mfma_f32_32x32x16_bf16 v[34:49], v[212:215], v[192:195], v[34:49]
	ds_read_b128 v[212:215], v191 offset:24608
	v_mfma_f32_32x32x16_bf16 v[34:49], v[216:219], v[196:199], v[34:49]
	v_mfma_f32_32x32x16_bf16 v[18:33], v[200:203], v[192:195], v[18:33]
	s_waitcnt lgkmcnt(2)
	v_mfma_f32_32x32x16_bf16 v[18:33], v[204:207], v[196:199], v[18:33]
	s_waitcnt lgkmcnt(1)
	v_mfma_f32_32x32x16_bf16 v[2:17], v[208:211], v[192:195], v[2:17]
	s_waitcnt lgkmcnt(0)
	v_mfma_f32_32x32x16_bf16 v[2:17], v[212:215], v[196:199], v[2:17]
	s_setprio 0
	s_bitcmp1_b32 s14, 0
	s_cselect_b32 s12, 0x6a00, 0
	s_add_i32 s15, s12, 0
	s_and_saveexec_b64 s[12:13], s[4:5]
	s_cbranch_execnz .LBB0_4663
	s_or_b64 exec, exec, s[12:13]
	s_and_saveexec_b64 s[12:13], s[6:7]
	s_cbranch_execnz .LBB0_4664
